# speedup vs baseline: 1.0108x; 1.0037x over previous
; __device__ __forceinline__ void partialSM(f32x16& p0, f32x16& p1, float& m_reg, float& mn, float& alpha) {
;     ...
;     const float mnL = -mn * C2;
; #pragma unroll
;     for (int r = 0; r < 16; ++r) p0[r] = fmaf(p0[r], C2, mnL);
; #pragma unroll
;     for (int r = 0; r < 16; ++r) p1[r] = fmaf(p1[r], C2, mnL);
.LBB0_414:
	v_mul_f32_e32 v181, 0xbdd53b94, v210
	v_fmamk_f32 v166, v82, 0x3dd53b94, v181
	v_fmamk_f32 v180, v83, 0x3dd53b94, v181
	v_fmamk_f32 v167, v84, 0x3dd53b94, v181
	v_fmamk_f32 v179, v85, 0x3dd53b94, v181
	v_fmamk_f32 v168, v86, 0x3dd53b94, v181
	v_fmamk_f32 v178, v87, 0x3dd53b94, v181
	v_fmamk_f32 v169, v88, 0x3dd53b94, v181
	v_fmamk_f32 v177, v89, 0x3dd53b94, v181
	v_fmamk_f32 v170, v90, 0x3dd53b94, v181
	v_fmamk_f32 v176, v91, 0x3dd53b94, v181
	v_fmamk_f32 v171, v92, 0x3dd53b94, v181
	v_fmamk_f32 v175, v93, 0x3dd53b94, v181
	v_fmamk_f32 v172, v94, 0x3dd53b94, v181
	v_fmamk_f32 v174, v95, 0x3dd53b94, v181
	v_fmamk_f32 v0, v96, 0x3dd53b94, v181
	v_fmamk_f32 v173, v97, 0x3dd53b94, v181
	v_pk_fma_f32 v[240:241], v[66:67], s[84:85], v[180:181] op_sel:[0,0,1] op_sel_hi:[1,0,1]
	v_pk_fma_f32 v[222:223], v[68:69], s[84:85], v[180:181] op_sel:[0,0,1] op_sel_hi:[1,0,1]
	v_pk_fma_f32 v[216:217], v[70:71], s[84:85], v[180:181] op_sel:[0,0,1] op_sel_hi:[1,0,1]
	v_pk_fma_f32 v[218:219], v[72:73], s[84:85], v[180:181] op_sel:[0,0,1] op_sel_hi:[1,0,1]
	v_pk_fma_f32 v[220:221], v[74:75], s[84:85], v[180:181] op_sel:[0,0,1] op_sel_hi:[1,0,1]
	v_pk_fma_f32 v[238:239], v[76:77], s[84:85], v[180:181] op_sel:[0,0,1] op_sel_hi:[1,0,1]
	v_pk_fma_f32 v[226:227], v[78:79], s[84:85], v[180:181] op_sel:[0,0,1] op_sel_hi:[1,0,1]
	v_pk_fma_f32 v[228:229], v[80:81], s[84:85], v[180:181] op_sel:[0,0,1] op_sel_hi:[1,0,1]
	s_waitcnt lgkmcnt(0)
	s_barrier
; __device__ __forceinline__ void partialSM(f32x16& p0, f32x16& p1, float& m_reg, float& mn, float& alpha) {
;     ...
;     for (int r = 0; r < 16; ++r) p0[r] = __builtin_amdgcn_exp2f(p0[r]);
; }
; __device__ __forceinline__ void finishSM(f32x16& p0, f32x16& p1, float alpha, float& l_reg, bf16x8& pa0, bf16x8& pa1, bf16x8& pa2, bf16x8& pa3) {
; #pragma unroll
;     for (int r = 0; r < 16; ++r) p1[r] = __builtin_amdgcn_exp2f(p1[r]);
;     float ps = 0;
; #pragma unroll
;     for (int r = 0; r < 16; ++r) ps += p0[r];
; #pragma unroll
;     for (int r = 0; r < 16; ++r) ps += p1[r];
;     { auto rr = __builtin_amdgcn_permlane32_swap(__float_as_uint(ps), __float_as_uint(ps), false, false);
;       ps = __uint_as_float(rr[0]) + __uint_as_float(rr[1]); }
;     l_reg = l_reg * alpha + ps;
;     ...
;     PK4(p0, 0, pa0); PK4(p0, 8, pa1); PK4(p1, 0, pa2); PK4(p1, 8, pa3);
; template <int KB>
; __device__ __forceinline__ void qkt(f32x16& p0, f32x16& p1, const char* lds, int r32, int hi, const bf16x8* qr) {
;     p0 = f32x16{}; p1 = f32x16{};
;     const char* kb = lds + AO_K + KB * SHM_K + KSWZ(r32, hi * 16); const char* rb = lds + AO_R + KB * SHM_R + RSWZ(r32, hi * 16);
; #pragma unroll
;     for (int d0 = 0; d0 < 8; ++d0) { const char* a = kb + d0 * 32;
;         bf16x8 b0 = *reinterpret_cast<const bf16x8*>(a);
;         bf16x8 b1 = *reinterpret_cast<const bf16x8*>(a + 32 * KPITCH);
;         p0 = __builtin_amdgcn_mfma_f32_32x32x16_bf16(b0, qr[d0], p0, 0, 0, 0);
;         p1 = __builtin_amdgcn_mfma_f32_32x32x16_bf16(b1, qr[d0], p1, 0, 0, 0); }
; #pragma unroll
;     for (int d0 = 0; d0 < 4; ++d0) { const char* a = rb + d0 * 32;
;         bf16x8 b0 = *reinterpret_cast<const bf16x8*>(a);
;         bf16x8 b1 = *reinterpret_cast<const bf16x8*>(a + 32 * RPITCH);
;         p0 = __builtin_amdgcn_mfma_f32_32x32x16_bf16(b0, qr[8 + d0], p0, 0, 0, 0);
;         p1 = __builtin_amdgcn_mfma_f32_32x32x16_bf16(b1, qr[8 + d0], p1, 0, 0, 0); }
	ds_read_b128 v[70:73], v200 offset:32768
	ds_read_b128 v[66:69], v200 offset:41472
	ds_read_b128 v[230:233], v200 offset:32800
	ds_read_b128 v[234:237], v200 offset:41504
	ds_read_b128 v[242:245], v200 offset:32832
	ds_read_b128 v[246:249], v200 offset:41536
	v_exp_f32_e32 v166, v166
	v_exp_f32_e32 v180, v180
	v_exp_f32_e32 v167, v167
	v_exp_f32_e32 v179, v179
	s_waitcnt lgkmcnt(4)
	v_mfma_f32_32x32x16_bf16 v[82:97], v[70:73], v[142:145], 0
	v_exp_f32_e32 v168, v168
	v_exp_f32_e32 v178, v178
	v_exp_f32_e32 v169, v169
	v_exp_f32_e32 v177, v177
	v_mfma_f32_32x32x16_bf16 v[66:81], v[66:69], v[142:145], 0
	v_exp_f32_e32 v170, v170
	v_exp_f32_e32 v176, v176
	v_exp_f32_e32 v171, v171
	v_exp_f32_e32 v175, v175
	s_waitcnt lgkmcnt(2)
	v_mfma_f32_32x32x16_bf16 v[66:81], v[234:237], v[138:141], v[66:81]
	v_exp_f32_e32 v172, v172
	v_exp_f32_e32 v174, v174
	v_exp_f32_e32 v173, v173
	v_exp_f32_e32 v0, v0
	v_mfma_f32_32x32x16_bf16 v[82:97], v[230:233], v[138:141], v[82:97]
	ds_read_b128 v[230:233], v200 offset:32864
	ds_read_b128 v[234:237], v200 offset:41568
	v_exp_f32_e32 v192, v222
	v_exp_f32_e32 v225, v226
	v_add_f32_e32 v215, v180, v166
	s_waitcnt lgkmcnt(2)
	v_mfma_f32_32x32x16_bf16 v[66:81], v[246:249], v[134:137], v[66:81]
	v_add_f32_e32 v215, v167, v215
	v_add_f32_e32 v215, v179, v215
	v_add_f32_e32 v215, v168, v215
	v_add_f32_e32 v215, v178, v215
	v_mfma_f32_32x32x16_bf16 v[82:97], v[242:245], v[134:137], v[82:97]
	ds_read_b128 v[242:245], v200 offset:32896
	ds_read_b128 v[246:249], v200 offset:41600
	v_add_f32_e32 v215, v169, v215
	v_add_f32_e32 v215, v177, v215
	v_add_f32_e32 v215, v170, v215
	v_add_f32_e32 v215, v176, v215
	s_waitcnt lgkmcnt(2)
	v_mfma_f32_32x32x16_bf16 v[66:81], v[234:237], v[130:133], v[66:81]
	v_add_f32_e32 v215, v171, v215
	v_add_f32_e32 v215, v175, v215
	v_exp_f32_e32 v190, v240
	v_add_f32_e32 v215, v172, v215
	v_mfma_f32_32x32x16_bf16 v[82:97], v[230:233], v[130:133], v[82:97]
	ds_read_b128 v[230:233], v200 offset:32928
	ds_read_b128 v[234:237], v200 offset:41632
	v_exp_f32_e32 v191, v241
	v_add_f32_e32 v215, v174, v215
	v_add_f32_e32 v215, v0, v215
	v_exp_f32_e32 v193, v223
	s_waitcnt lgkmcnt(2)
	v_mfma_f32_32x32x16_bf16 v[66:81], v[246:249], v[126:129], v[66:81]
	v_add_f32_e32 v215, v173, v215
	v_exp_f32_e32 v223, v216
	v_add_f32_e32 v215, v190, v215
	v_exp_f32_e32 v224, v217
	v_mfma_f32_32x32x16_bf16 v[82:97], v[242:245], v[126:129], v[82:97]
	ds_read_b128 v[242:245], v200 offset:32960
	ds_read_b128 v[246:249], v200 offset:41664
	v_add_f32_e32 v215, v191, v215
	v_exp_f32_e32 v217, v218
	v_add_f32_e32 v215, v192, v215
	v_exp_f32_e32 v218, v219
	s_waitcnt lgkmcnt(2)
	v_mfma_f32_32x32x16_bf16 v[66:81], v[234:237], v[122:125], v[66:81]
	v_add_f32_e32 v215, v193, v215
	v_exp_f32_e32 v219, v220
	v_add_f32_e32 v215, v223, v215
	v_mfma_f32_32x32x16_bf16 v[82:97], v[230:233], v[122:125], v[82:97]
	ds_read_b128 v[230:233], v200 offset:32992
	ds_read_b128 v[234:237], v200 offset:41696
	v_exp_f32_e32 v220, v221
	v_add_f32_e32 v215, v224, v215
	v_exp_f32_e32 v221, v238
	v_add_f32_e32 v215, v217, v215
	s_waitcnt lgkmcnt(2)
	v_mfma_f32_32x32x16_bf16 v[66:81], v[246:249], v[118:121], v[66:81]
	v_exp_f32_e32 v222, v239
	v_add_f32_e32 v215, v218, v215
	v_add_f32_e32 v215, v219, v215
	v_exp_f32_e32 v226, v227
	v_mfma_f32_32x32x16_bf16 v[82:97], v[242:245], v[118:121], v[82:97]
	ds_read_b128 v[242:245], v204
	ds_read_b128 v[246:249], v204 offset:4608
	v_add_f32_e32 v215, v220, v215
	v_exp_f32_e32 v227, v228
	v_add_f32_e32 v215, v221, v215
	v_exp_f32_e32 v181, v229
	s_waitcnt lgkmcnt(2)
	v_mfma_f32_32x32x16_bf16 v[66:81], v[234:237], v[110:113], v[66:81]
	v_add_f32_e32 v215, v222, v215
	v_add_f32_e32 v215, v225, v215
	v_add_f32_e32 v215, v226, v215
	v_add_f32_e32 v215, v227, v215
	v_mfma_f32_32x32x16_bf16 v[82:97], v[230:233], v[110:113], v[82:97]
	ds_read_b128 v[230:233], v204 offset:32
	ds_read_b128 v[234:237], v204 offset:4640
	v_add_f32_e32 v215, v181, v215
	v_mov_b32_e32 v216, v215
	v_cvt_pk_bf16_f32 v166, v166, v180
	v_cvt_pk_bf16_f32 v167, v167, v179
	s_waitcnt lgkmcnt(2)
	v_mfma_f32_32x32x16_bf16 v[66:81], v[246:249], v[114:117], v[66:81]
	v_cvt_pk_bf16_f32 v168, v168, v178
	v_cvt_pk_bf16_f32 v169, v169, v177
	v_cvt_pk_bf16_f32 v170, v170, v176
	v_cvt_pk_bf16_f32 v171, v171, v175
	v_mfma_f32_32x32x16_bf16 v[82:97], v[242:245], v[114:117], v[82:97]
	ds_read_b128 v[242:245], v204 offset:64
	ds_read_b128 v[246:249], v204 offset:4672
	v_cvt_pk_bf16_f32 v172, v172, v174
	v_cvt_pk_bf16_f32 v173, v0, v173
	v_cvt_pk_bf16_f32 v174, v190, v191
	v_cvt_pk_bf16_f32 v175, v192, v193
	s_waitcnt lgkmcnt(2)
	v_mfma_f32_32x32x16_bf16 v[82:97], v[230:233], v[106:109], v[82:97]
	v_cvt_pk_bf16_f32 v176, v223, v224
	v_cvt_pk_bf16_f32 v177, v217, v218
	v_cvt_pk_bf16_f32 v178, v219, v220
	v_cvt_pk_bf16_f32 v179, v221, v222
	v_mfma_f32_32x32x16_bf16 v[66:81], v[234:237], v[106:109], v[66:81]
	ds_read_b128 v[230:233], v204 offset:96
	ds_read_b128 v[234:237], v204 offset:4704
	v_cvt_pk_bf16_f32 v180, v225, v226
	v_cvt_pk_bf16_f32 v181, v227, v181
	v_permlane32_swap_b32_e32 v215, v216
	v_permlane32_swap_b32_e32 v166, v168
	s_waitcnt lgkmcnt(2)
	v_mfma_f32_32x32x16_bf16 v[82:97], v[242:245], v[102:105], v[82:97]
	v_permlane32_swap_b32_e32 v167, v169
	v_permlane32_swap_b32_e32 v170, v172
	v_permlane32_swap_b32_e32 v171, v173
	v_permlane32_swap_b32_e32 v174, v176
	v_mfma_f32_32x32x16_bf16 v[66:81], v[246:249], v[102:105], v[66:81]
	v_permlane32_swap_b32_e32 v175, v177
	v_permlane32_swap_b32_e32 v178, v180
	v_permlane32_swap_b32_e32 v179, v181
	s_waitcnt lgkmcnt(0)
	v_mfma_f32_32x32x16_bf16 v[82:97], v[230:233], v[98:101], v[82:97]
	v_mfma_f32_32x32x16_bf16 v[66:81], v[234:237], v[98:101], v[66:81]
	ds_read_b64_tr_b16 v[218:219], v194 offset:0x4000
	ds_read_b64_tr_b16 v[220:221], v194 offset:0x4800
	ds_read_b64_tr_b16 v[222:223], v194 offset:0x5000
	ds_read_b64_tr_b16 v[224:225], v194 offset:0x5800
	ds_read_b64_tr_b16 v[226:227], v194 offset:0x6000
	ds_read_b64_tr_b16 v[228:229], v194 offset:0x6800
	ds_read_b64_tr_b16 v[230:231], v194 offset:0x7000
	ds_read_b64_tr_b16 v[232:233], v194 offset:0x7800
	s_add_i32 s6, s82, 1
	s_cmp_lt_u32 s6, s83
	s_cselect_b64 s[90:91], -1, 0
	s_cmp_ge_u32 s6, s83
	s_cbranch_scc1 .LBB0_416
	s_add_u32 s8, s74, 0x1b98c000
	s_addc_u32 s9, s75, 0
	s_add_u32 s10, s74, 0x1b98e000
	s_addc_u32 s11, s75, 0
	s_add_u32 s12, s80, 0x18886000
	s_addc_u32 s13, s81, 0
	s_add_u32 s14, s74, 0x1d98c000
	s_addc_u32 s15, s75, 0
	s_add_u32 s16, s74, 0x1d98e000
	s_addc_u32 s17, s75, 0
	global_load_dwordx4 v[154:157], v201, s[8:9]
	global_load_dwordx4 v[158:161], v201, s[10:11]
	global_load_dwordx4 v[162:165], v199, s[12:13]
	global_load_dwordx4 v[146:149], v201, s[14:15]
	global_load_dwordx4 v[150:153], v201, s[16:17]
